# postepi2: first two counted waits of the first K-iteration after an epilogue leave the epilogue stores in flight (vmcnt 24/16 in-proj, 32 out-proj), on top of v72
# baseline (speedup 1.0000x reference)
; #define PG8_STAGE(bufoff, gbase, voff) do { _Pragma("unroll") for (int _i = 0; _i < 2; ++_i) \
;         __builtin_amdgcn_global_load_lds((const unsigned*)((const char*)(gbase) + (voff)[_i]), (PG8_LAS unsigned*)(lds + (bufoff) + ldsw + _i * 8192), 16, 0, 0); } while (0)
; #define PG8_LDA(dst, b, h) do { _Pragma("unroll") for (int m = 0; m < 4; ++m) _Pragma("unroll") for (int k = 0; k < 2; ++k) dst[m][k] = *(const PG8_LAS bf16x8*)(lds + PG8_SA(b, h) + aoff + m * 2048 + k * 1024); } while (0)
; #define PG8_LDB(dst, b, h) do { _Pragma("unroll") for (int n = 0; n < 2; ++n) _Pragma("unroll") for (int k = 0; k < 2; ++k) dst[n][k] = *(const PG8_LAS bf16x8*)(lds + PG8_SB(b, h) + boff + n * 2048 + k * 1024); } while (0)
; #define PG8_MMA(ai, bj, At, Bt) do { __builtin_amdgcn_s_setprio(1); _Pragma("unroll") for (int m = 0; m < 4; ++m) _Pragma("unroll") for (int n = 0; n < 2; ++n) _Pragma("unroll") for (int k = 0; k < 2; ++k) \
;         acc[ai][bj][m][n] = __builtin_amdgcn_mfma_f32_16x16x32_bf16(Bt[n][k], At[m][k], acc[ai][bj][m][n], 0, 0, 0); __builtin_amdgcn_s_setprio(0); } while (0)
; #define PG8_WAIT_V(n) asm volatile("s_waitcnt vmcnt(" #n ")" ::: "memory")
; #define PG8_WAIT_L(n) asm volatile("s_waitcnt lgkmcnt(" #n ")" ::: "memory")
; #define PG8_BAR __builtin_amdgcn_s_barrier()
; #define PG8_SCHED __builtin_amdgcn_sched_barrier(0)
; template <class Epi, class Sched, bool ALIGN_EPI = false, bool SP2 = true>
; __device__ __forceinline__ void gemm_phase(PG8_LAS unsigned char* lds, const Gemm g, const Sched& S, const Epi& E, int wave_s) {
;     ...
;             PG8_LDB(B0, 0, 0); PG8_LDB(B1, 0, 1); PG8_SCHED; PG8_LDA(At, 0, 0); PG8_STAGE(PG8_SA(1, 1), a1 + hstepA, voffA);
;             PG8_WAIT_V(8); PG8_WAIT_L(0); PG8_BAR; PG8_MMA(0, 0, At, B0); PG8_MMA(0, 1, At, B1); PG8_BAR; PG8_SCHED;
.LBB0_345:
	s_add_u32 s6, s4, 0xfff80080
	s_addc_u32 s7, s5, -1
	s_add_i32 s73, 0, 0x10000
	s_cmp_eq_u32 s72, 28
	s_cselect_b32 s11, s23, s7
	s_cselect_b32 s10, s28, s6
	v_add_u32_e32 v144, s73, v139
	s_cselect_b32 s7, s21, s46
	s_cselect_b32 s6, s29, s33
	s_add_i32 s76, 0, 0x14000
	ds_read_b128 v[154:157], v144
	ds_read_b128 v[158:161], v144 offset:1024
	ds_read_b128 v[162:165], v144 offset:2048
	ds_read_b128 v[166:169], v144 offset:3072
	v_add_u32_e32 v144, s76, v139
	ds_read_b128 v[176:179], v144
	ds_read_b128 v[180:183], v144 offset:1024
	ds_read_b128 v[184:187], v144 offset:2048
	ds_read_b128 v[188:191], v144 offset:3072
	v_lshl_add_u64 v[144:145], s[4:5], 0, v[142:143]
	s_add_i32 m0, s35, 0xc000
	ds_read_b128 v[192:195], v174
	ds_read_b128 v[196:199], v174 offset:1024
	ds_read_b128 v[200:203], v174 offset:2048
	ds_read_b128 v[204:207], v174 offset:3072
	ds_read_b128 v[208:211], v174 offset:4096
	ds_read_b128 v[212:215], v174 offset:5120
	ds_read_b128 v[216:219], v174 offset:6144
	ds_read_b128 v[220:223], v174 offset:7168
	global_load_lds_dwordx4 v[144:145], off
	v_lshl_add_u64 v[144:145], s[4:5], 0, v[140:141]
	s_add_i32 m0, s35, 0xe000
	s_nop 0
	global_load_lds_dwordx4 v[144:145], off
	s_cmp_lg_u32 s72, -2
	s_cbranch_scc1 .Lpf_g1_w0n
	s_cmp_eq_u32 s3, 0
	s_cbranch_scc1 .Lpf_g1_w0n
	s_cmp_eq_u32 s32, 24
	s_cbranch_scc0 .Lpf_g1_w0z
	s_waitcnt vmcnt(24)
	s_branch .Lpf_g1_w0d
.Lpf_g1_w0z:
	s_waitcnt vmcnt(16)
	s_branch .Lpf_g1_w0d

; #define PG8_STAGE(bufoff, gbase, voff) do { _Pragma("unroll") for (int _i = 0; _i < 2; ++_i) \
;         __builtin_amdgcn_global_load_lds((const unsigned*)((const char*)(gbase) + (voff)[_i]), (PG8_LAS unsigned*)(lds + (bufoff) + ldsw + _i * 8192), 16, 0, 0); } while (0)
; #define PG8_LDA(dst, b, h) do { _Pragma("unroll") for (int m = 0; m < 4; ++m) _Pragma("unroll") for (int k = 0; k < 2; ++k) dst[m][k] = *(const PG8_LAS bf16x8*)(lds + PG8_SA(b, h) + aoff + m * 2048 + k * 1024); } while (0)
; #define PG8_MMA(ai, bj, At, Bt) do { __builtin_amdgcn_s_setprio(1); _Pragma("unroll") for (int m = 0; m < 4; ++m) _Pragma("unroll") for (int n = 0; n < 2; ++n) _Pragma("unroll") for (int k = 0; k < 2; ++k) \
;         acc[ai][bj][m][n] = __builtin_amdgcn_mfma_f32_16x16x32_bf16(Bt[n][k], At[m][k], acc[ai][bj][m][n], 0, 0, 0); __builtin_amdgcn_s_setprio(0); } while (0)
; #define PG8_WAIT_V(n) asm volatile("s_waitcnt vmcnt(" #n ")" ::: "memory")
; #define PG8_WAIT_L(n) asm volatile("s_waitcnt lgkmcnt(" #n ")" ::: "memory")
; #define PG8_BAR __builtin_amdgcn_s_barrier()
; #define PG8_SCHED __builtin_amdgcn_sched_barrier(0)
; template <class Epi, class Sched, bool ALIGN_EPI = false, bool SP2 = true>
; __device__ __forceinline__ void gemm_phase(PG8_LAS unsigned char* lds, const Gemm g, const Sched& S, const Epi& E, int wave_s) {
;     ...
;             PG8_WAIT_V(8); PG8_WAIT_L(0); PG8_BAR; PG8_MMA(0, 0, At, B0); PG8_MMA(0, 1, At, B1); PG8_BAR; PG8_SCHED;
;             PG8_LDA(At, 0, 1); PG8_STAGE(PG8_SB(0, 0), b2, voffB); PG8_STAGE(PG8_SB(0, 1), b2 + hstepB, voffB); PG8_STAGE(PG8_SA(0, 0), a2, voffA);
;             PG8_WAIT_V(8); PG8_WAIT_L(0); PG8_BAR; PG8_MMA(1, 0, At, B0); PG8_MMA(1, 1, At, B1); PG8_BAR; PG8_SCHED;
.Lpf_g1_w0d:
	s_waitcnt lgkmcnt(0)
	s_barrier
	s_setprio 1
	v_mfma_f32_16x16x32_bf16 v[126:129], v[154:157], v[192:195], v[126:129]
	v_mfma_f32_16x16x32_bf16 v[122:125], v[162:165], v[192:195], v[122:125]
	v_mfma_f32_16x16x32_bf16 v[110:113], v[154:157], v[200:203], v[110:113]
	v_mfma_f32_16x16x32_bf16 v[106:109], v[162:165], v[200:203], v[106:109]
	v_mfma_f32_16x16x32_bf16 v[94:97], v[154:157], v[208:211], v[94:97]
	v_mfma_f32_16x16x32_bf16 v[90:93], v[162:165], v[208:211], v[90:93]
	v_mfma_f32_16x16x32_bf16 v[78:81], v[154:157], v[216:219], v[78:81]
	v_mfma_f32_16x16x32_bf16 v[74:77], v[162:165], v[216:219], v[74:77]
	v_mfma_f32_16x16x32_bf16 v[126:129], v[158:161], v[196:199], v[126:129]
	v_mfma_f32_16x16x32_bf16 v[122:125], v[166:169], v[196:199], v[122:125]
	v_mfma_f32_16x16x32_bf16 v[110:113], v[158:161], v[204:207], v[110:113]
	v_mfma_f32_16x16x32_bf16 v[106:109], v[166:169], v[204:207], v[106:109]
	v_mfma_f32_16x16x32_bf16 v[94:97], v[158:161], v[212:215], v[94:97]
	v_mfma_f32_16x16x32_bf16 v[90:93], v[166:169], v[212:215], v[90:93]
	v_mfma_f32_16x16x32_bf16 v[78:81], v[158:161], v[220:223], v[78:81]
	v_mfma_f32_16x16x32_bf16 v[74:77], v[166:169], v[220:223], v[74:77]
	v_mfma_f32_16x16x32_bf16 v[118:121], v[176:179], v[192:195], v[118:121]
	v_mfma_f32_16x16x32_bf16 v[114:117], v[184:187], v[192:195], v[114:117]
	v_mfma_f32_16x16x32_bf16 v[102:105], v[176:179], v[200:203], v[102:105]
	v_mfma_f32_16x16x32_bf16 v[98:101], v[184:187], v[200:203], v[98:101]
	v_mfma_f32_16x16x32_bf16 v[86:89], v[176:179], v[208:211], v[86:89]
	v_mfma_f32_16x16x32_bf16 v[82:85], v[184:187], v[208:211], v[82:85]
	v_mfma_f32_16x16x32_bf16 v[70:73], v[176:179], v[216:219], v[70:73]
	v_mfma_f32_16x16x32_bf16 v[66:69], v[184:187], v[216:219], v[66:69]
	v_mfma_f32_16x16x32_bf16 v[118:121], v[180:183], v[196:199], v[118:121]
	v_mfma_f32_16x16x32_bf16 v[114:117], v[188:191], v[196:199], v[114:117]
	v_mfma_f32_16x16x32_bf16 v[102:105], v[180:183], v[204:207], v[102:105]
	v_mfma_f32_16x16x32_bf16 v[98:101], v[188:191], v[204:207], v[98:101]
	v_mfma_f32_16x16x32_bf16 v[86:89], v[180:183], v[212:215], v[86:89]
	v_mfma_f32_16x16x32_bf16 v[82:85], v[188:191], v[212:215], v[82:85]
	v_mfma_f32_16x16x32_bf16 v[70:73], v[180:183], v[220:223], v[70:73]
	v_mfma_f32_16x16x32_bf16 v[66:69], v[188:191], v[220:223], v[66:69]
	s_setprio 0
	s_barrier
	s_add_i32 s73, s73, s34
	v_lshl_add_u64 v[144:145], s[6:7], 0, v[134:135]
	s_mov_b32 m0, s73
	ds_read_b128 v[192:195], v174 offset:16384
	ds_read_b128 v[196:199], v174 offset:17408
	ds_read_b128 v[200:203], v174 offset:18432
	ds_read_b128 v[204:207], v174 offset:19456
	ds_read_b128 v[208:211], v174 offset:20480
	ds_read_b128 v[212:215], v174 offset:21504
	ds_read_b128 v[216:219], v174 offset:22528
	ds_read_b128 v[220:223], v174 offset:23552
	global_load_lds_dwordx4 v[144:145], off
	s_add_i32 m0, s73, 0x2000
	s_add_u32 s74, s6, 0x80000
	v_lshl_add_u64 v[170:171], s[6:7], 0, v[130:131]
	s_addc_u32 s75, s7, 0
	s_add_i32 s73, s76, s34
	global_load_lds_dwordx4 v[170:171], off
	v_lshl_add_u64 v[224:225], s[74:75], 0, v[134:135]
	s_mov_b32 m0, s73
	v_lshl_add_u64 v[226:227], s[10:11], 0, v[132:133]
	global_load_lds_dwordx4 v[224:225], off
	v_lshl_add_u64 v[224:225], s[74:75], 0, v[130:131]
	s_add_i32 m0, s73, 0x2000
	s_nop 0
	global_load_lds_dwordx4 v[224:225], off
	v_lshl_add_u64 v[224:225], s[10:11], 0, v[136:137]
	s_mov_b32 m0, s35
	s_nop 0
	global_load_lds_dwordx4 v[224:225], off
	s_mov_b32 m0, s37
	s_nop 0
	global_load_lds_dwordx4 v[226:227], off
	s_cmp_lg_u32 s72, -2
	s_cbranch_scc1 .Lpf_g1_w1n
	s_cmp_eq_u32 s3, 0
	s_cbranch_scc1 .Lpf_g1_w1n
	s_cmp_eq_u32 s32, 24
	s_cbranch_scc0 .Lpf_g1_w1z
	s_waitcnt vmcnt(24)
	s_branch .Lpf_g1_w1d

; #define GAS __attribute__((address_space(1)))
;     __device__ __forceinline__ void operator()(const f32x4 (&acc)[2][2][4][2], const Unit& u, int wr, int wc, int fr, int fq, const PG8_LAS float* tab) const {
;         const int pn = u.pn; const bool is_rope = (pn < 4) || (pn == 8); const bool is_z = (pn >= 18); const float qs = (pn < 4) ? 0.125f : 1.0f;
; #pragma unroll
;         for (int ai = 0; ai < 2; ++ai)
; #pragma unroll
;             for (int m = 0; m < 4; ++m) {
;                 const int row = u.pm * BM + ai * HALF + wr * 64 + m * 16 + fr;
;                 const float rs = rsqrtf(tab[ai * HALF + wr * 64 + m * 16 + fr] * (1.0f / 2048.0f) + 1e-6f);
;                 const int pos = row < 16384 ? (row & 8191) : (row - 16384);
;                 GAS bf16_t* rowp = (GAS bf16_t*)P + (size_t)row * 5120;
;                 if (is_z) {
.LBB0_348:
	s_mov_b32 s32, 24
	s_cmp_lt_i32 s0, 4
	s_cbranch_scc1 .Lei_rope
	s_cmp_eq_u32 s0, 8
	s_cbranch_scc0 .Lei_plain_test

; #define GAS __attribute__((address_space(1)))
; __device__ __forceinline__ unsigned cvt_pk_bf16(float lo, float hi) { unsigned r; asm volatile("v_cvt_pk_bf16_f32 %0, %1, %2" : "=v"(r) : "v"(lo), "v"(hi)); return r; }
;     __device__ __forceinline__ void operator()(const f32x4 (&acc)[2][2][4][2], const Unit& u, int wr, int wc, int fr, int fq, const PG8_LAS float* tab) const {
;     ...
;                 if (is_z) {
;                     const f32x4 z0 = (acc[ai][0][m][0] * rs) * (acc[ai][1][m][0] * rs), z1 = (acc[ai][0][m][1] * rs) * (acc[ai][1][m][1] * rs);
;                     u32x4 w; w.x = cvt_pk_bf16(z0[0], z0[1]); w.y = cvt_pk_bf16(z0[2], z0[3]); w.z = cvt_pk_bf16(z1[0], z1[1]); w.w = cvt_pk_bf16(z1[2], z1[3]);
;                     *(GAS u32x4*)(rowp + 4608 + (pn - 18) * 128 + wc * 32 + 8 * fq) = w;
;                     continue;
.Lei_zmark:
	s_mov_b32 s32, 16

; #define PG8_STAGE(bufoff, gbase, voff) do { _Pragma("unroll") for (int _i = 0; _i < 2; ++_i) \
;         __builtin_amdgcn_global_load_lds((const unsigned*)((const char*)(gbase) + (voff)[_i]), (PG8_LAS unsigned*)(lds + (bufoff) + ldsw + _i * 8192), 16, 0, 0); } while (0)
; #define PG8_LDA(dst, b, h) do { _Pragma("unroll") for (int m = 0; m < 4; ++m) _Pragma("unroll") for (int k = 0; k < 2; ++k) dst[m][k] = *(const PG8_LAS bf16x8*)(lds + PG8_SA(b, h) + aoff + m * 2048 + k * 1024); } while (0)
; #define PG8_LDB(dst, b, h) do { _Pragma("unroll") for (int n = 0; n < 2; ++n) _Pragma("unroll") for (int k = 0; k < 2; ++k) dst[n][k] = *(const PG8_LAS bf16x8*)(lds + PG8_SB(b, h) + boff + n * 2048 + k * 1024); } while (0)
; #define PG8_MMA(ai, bj, At, Bt) do { __builtin_amdgcn_s_setprio(1); _Pragma("unroll") for (int m = 0; m < 4; ++m) _Pragma("unroll") for (int n = 0; n < 2; ++n) _Pragma("unroll") for (int k = 0; k < 2; ++k) \
;         acc[ai][bj][m][n] = __builtin_amdgcn_mfma_f32_16x16x32_bf16(Bt[n][k], At[m][k], acc[ai][bj][m][n], 0, 0, 0); __builtin_amdgcn_s_setprio(0); } while (0)
; #define PG8_WAIT_V(n) asm volatile("s_waitcnt vmcnt(" #n ")" ::: "memory")
; #define PG8_WAIT_L(n) asm volatile("s_waitcnt lgkmcnt(" #n ")" ::: "memory")
; #define PG8_BAR __builtin_amdgcn_s_barrier()
; #define PG8_SCHED __builtin_amdgcn_sched_barrier(0)
; template <class Epi, class Sched, bool ALIGN_EPI = false, bool SP2 = true>
; __device__ __forceinline__ void gemm_phase(PG8_LAS unsigned char* lds, const Gemm g, const Sched& S, const Epi& E, int wave_s) {
;     ...
;             PG8_LDB(B0, 0, 0); PG8_LDB(B1, 0, 1); PG8_SCHED; PG8_LDA(At, 0, 0); PG8_STAGE(PG8_SA(1, 1), a1 + hstepA, voffA);
;             PG8_WAIT_V(8); PG8_WAIT_L(0); PG8_BAR; PG8_MMA(0, 0, At, B0); PG8_MMA(0, 1, At, B1); PG8_BAR; PG8_SCHED;
.LBB0_608:
	s_add_u32 s6, s24, 0x100
	s_addc_u32 s7, s25, 0
	s_add_i32 s75, 0, 0x10000
	s_cmp_eq_u32 s74, 28
	s_cselect_b32 s29, s21, s7
	s_cselect_b32 s28, s20, s6
	v_add_u32_e32 v146, s75, v170
	s_cselect_b32 s27, s19, s73
	s_cselect_b32 s26, s33, s72
	s_add_i32 s76, 0, 0x14000
	ds_read_b128 v[130:133], v146
	ds_read_b128 v[134:137], v146 offset:1024
	ds_read_b128 v[158:161], v146 offset:2048
	ds_read_b128 v[162:165], v146 offset:3072
	v_add_u32_e32 v146, s76, v170
	ds_read_b128 v[166:169], v146
	ds_read_b128 v[176:179], v146 offset:1024
	ds_read_b128 v[180:183], v146 offset:2048
	ds_read_b128 v[184:187], v146 offset:3072
	v_lshl_add_u64 v[146:147], s[24:25], 0, v[156:157]
	s_add_i32 m0, s35, 0xc000
	ds_read_b128 v[188:191], v174
	ds_read_b128 v[192:195], v174 offset:1024
	ds_read_b128 v[196:199], v174 offset:2048
	ds_read_b128 v[200:203], v174 offset:3072
	ds_read_b128 v[204:207], v174 offset:4096
	ds_read_b128 v[208:211], v174 offset:5120
	ds_read_b128 v[212:215], v174 offset:6144
	ds_read_b128 v[216:219], v174 offset:7168
	global_load_lds_dwordx4 v[146:147], off
	v_lshl_add_u64 v[146:147], s[24:25], 0, v[154:155]
	s_add_i32 m0, s35, 0xe000
	s_nop 0
	global_load_lds_dwordx4 v[146:147], off
	s_cmp_lg_u32 s74, -2
	s_cbranch_scc1 .Lpf_g3_w0n
	s_cmp_eq_u32 s1, 0
	s_cbranch_scc1 .Lpf_g3_w0n
	s_waitcnt vmcnt(32)
	s_branch .Lpf_g3_w0d

; #define PG8_STAGE(bufoff, gbase, voff) do { _Pragma("unroll") for (int _i = 0; _i < 2; ++_i) \
;         __builtin_amdgcn_global_load_lds((const unsigned*)((const char*)(gbase) + (voff)[_i]), (PG8_LAS unsigned*)(lds + (bufoff) + ldsw + _i * 8192), 16, 0, 0); } while (0)
; #define PG8_LDA(dst, b, h) do { _Pragma("unroll") for (int m = 0; m < 4; ++m) _Pragma("unroll") for (int k = 0; k < 2; ++k) dst[m][k] = *(const PG8_LAS bf16x8*)(lds + PG8_SA(b, h) + aoff + m * 2048 + k * 1024); } while (0)
; #define PG8_LDB(dst, b, h) do { _Pragma("unroll") for (int n = 0; n < 2; ++n) _Pragma("unroll") for (int k = 0; k < 2; ++k) dst[n][k] = *(const PG8_LAS bf16x8*)(lds + PG8_SB(b, h) + boff + n * 2048 + k * 1024); } while (0)
; #define PG8_MMA(ai, bj, At, Bt) do { __builtin_amdgcn_s_setprio(1); _Pragma("unroll") for (int m = 0; m < 4; ++m) _Pragma("unroll") for (int n = 0; n < 2; ++n) _Pragma("unroll") for (int k = 0; k < 2; ++k) \
;         acc[ai][bj][m][n] = __builtin_amdgcn_mfma_f32_16x16x32_bf16(Bt[n][k], At[m][k], acc[ai][bj][m][n], 0, 0, 0); __builtin_amdgcn_s_setprio(0); } while (0)
; #define PG8_WAIT_V(n) asm volatile("s_waitcnt vmcnt(" #n ")" ::: "memory")
; #define PG8_WAIT_L(n) asm volatile("s_waitcnt lgkmcnt(" #n ")" ::: "memory")
; #define PG8_BAR __builtin_amdgcn_s_barrier()
; #define PG8_SCHED __builtin_amdgcn_sched_barrier(0)
; template <class Epi, class Sched, bool ALIGN_EPI = false, bool SP2 = true>
; __device__ __forceinline__ void gemm_phase(PG8_LAS unsigned char* lds, const Gemm g, const Sched& S, const Epi& E, int wave_s) {
;     ...
;             PG8_WAIT_V(8); PG8_WAIT_L(0); PG8_BAR; PG8_MMA(1, 0, At, B0); PG8_MMA(1, 1, At, B1); PG8_BAR; PG8_SCHED;
;             PG8_LDB(B0, 1, 0); PG8_LDB(B1, 1, 1); PG8_SCHED; PG8_LDA(At, 1, 0); PG8_STAGE(PG8_SA(0, 1), a2 + hstepA, voffA);
.Lrf_join:
	s_cmp_lg_u32 s74, -2
	s_cbranch_scc1 .Lpf_g3_w1n
	s_cmp_eq_u32 s1, 0
	s_cbranch_scc1 .Lpf_g3_w1n
	s_waitcnt vmcnt(32)
	s_branch .Lpf_g3_w1d
